# cross-attention: both Q chunks loaded together with the last K chunk
# speedup vs baseline: 1.0053x; 1.0053x over previous
; #define LAS __attribute__((address_space(3)))
; __device__ __forceinline__ unsigned pk2(float lo, float hi) { const f32x2_t v = {lo, hi}; const bf16x2_t b = __builtin_convertvector(v, bf16x2_t); return __builtin_bit_cast(unsigned, b); }
; __device__ __forceinline__ void xattn_item(ldsp lds, const bf16_t* QM, const float* Kg, const float* Vg, const bf16_t* Kb, const bf16_t* Vtb, int row0, int tvalid, int hm, bf16_t* OM, int tid, int lane, int wave) {
;     ...
;         for (int jj = 0; jj < 8; ++jj) { const int cidx = tid + 512 * jj, m = cidx >> 4, dc = cidx & 15; *(LAS u32x4*)(lds + KM + m * 272 + dc * 16) = *(const u32x4*)(Kb + m * 128 + dc * 8); }
;     } else {
; #pragma unroll
;         for (int jj = 0; jj < 8; ++jj) { const int cidx = tid + 512 * jj, m = cidx >> 4, dc = cidx & 15; const float* p = Kg + (size_t)m * 512 + dc * 8;
;             const f32x4 a = *(const f32x4*)p, b = *(const f32x4*)(p + 4);
;             *(LAS u32x4*)(lds + KM + m * 272 + dc * 16) = (u32x4){pk2(a[0], a[1]), pk2(a[2], a[3]), pk2(b[0], b[1]), pk2(b[2], b[3])}; } }
; #pragma unroll
;     for (int jj = 0; jj < 2; ++jj) { const int cidx = tid + 512 * jj, t = cidx >> 4, dc = cidx & 15; u32x4 w = {0u, 0u, 0u, 0u};
;         if (t < tvalid) w = *(const u32x4*)(QM + (size_t)(row0 + t) * 512 + hm * 128 + dc * 8);
;         *(LAS u32x4*)(lds + QS + t * 272 + dc * 16) = w; }
;     float vr0[32], vr1[32]; u32x4 vq[8];
;     if (Vtb) {
; #pragma unroll
;         for (int jj = 0; jj < 8; ++jj) { const int cidx = tid + 512 * jj, d = cidx >> 5, mc = cidx & 31; vq[jj] = *(const u32x4*)(Vtb + d * 256 + mc * 8); }
.LBB0_2172:
	v_mad_u64_u32 v[4:5], s[2:3], v7, s75, v[4:5]
	s_lshl_b32 s12, s86, 1
	s_add_u32 s2, s14, s12
	s_addc_u32 s3, s15, 0
	v_lshl_add_u64 v[10:11], s[2:3], 0, v[192:193]
	v_mov_b32_e32 v142, 0
	v_mov_b32_e32 v143, 0
	v_mov_b32_e32 v144, 0
	v_mov_b32_e32 v145, 0
	v_mov_b32_e32 v146, 0
	v_mov_b32_e32 v147, 0
	v_mov_b32_e32 v148, 0
	v_mov_b32_e32 v149, 0
	v_cmp_gt_i32_e32 vcc, s34, v8
	s_and_saveexec_b64 s[2:3], vcc
	s_cbranch_execz .LBB0_2174
	v_add_u32_e32 v150, s31, v8
	v_ashrrev_i32_e32 v151, 31, v150
	v_lshlrev_b64 v[150:151], 10, v[150:151]
	v_lshl_add_u64 v[150:151], v[10:11], 0, v[150:151]
	global_load_dwordx4 v[142:145], v[150:151], off
.LBB0_2174:
	s_or_b64 exec, exec, s[2:3]
	v_cmp_gt_i32_e32 vcc, s34, v6
	s_and_saveexec_b64 s[2:3], vcc
	s_cbranch_execz .LBB0_2176
	v_add_u32_e32 v152, s31, v6
	v_ashrrev_i32_e32 v153, 31, v152
	v_lshlrev_b64 v[152:153], 10, v[152:153]
	v_lshl_add_u64 v[152:153], v[10:11], 0, v[152:153]
	global_load_dwordx4 v[146:149], v[152:153], off
.LBB0_2176:
	s_or_b64 exec, exec, s[2:3]
	s_add_i32 s13, 0, 0x11000
	v_add_u32_e32 v12, s13, v28
	v_mad_u64_u32 v[8:9], s[2:3], v8, s75, v[12:13]
	v_mad_u64_u32 v[154:155], s[2:3], v6, s75, v[12:13]
	s_cmp_lg_u64 s[10:11], 0
	s_waitcnt vmcnt(0)
	ds_write_b128 v4, v[0:3]
	ds_write_b128 v8, v[142:145]
	ds_write_b128 v154, v[146:149]
	s_cselect_b64 s[2:3], -1, 0
	v_lshlrev_b32_e32 v0, 4, v81
	s_and_b64 vcc, exec, s[2:3]
	v_and_b32_e32 v192, 0x1f0, v0
	s_cbranch_vccz .LBB0_2178
	v_lshlrev_b32_e32 v0, 3, v81
	v_and_b32_e32 v30, 0xffffff00, v0
	v_lshl_add_u64 v[28:29], s[10:11], 0, v[192:193]
	v_ashrrev_i32_e32 v31, 31, v30
	v_lshl_add_u64 v[0:1], v[30:31], 1, v[28:29]
	v_add_u32_e32 v2, 0x1000, v30
	v_add_u32_e32 v8, 0x2000, v30
	v_add_u32_e32 v10, 0x3000, v30
	v_add_u32_e32 v20, 0x4000, v30
	v_add_u32_e32 v22, 0x5000, v30
	v_add_u32_e32 v32, 0x6000, v30
	v_add_u32_e32 v30, 0x7000, v30
	v_ashrrev_i32_e32 v3, 31, v2
	v_ashrrev_i32_e32 v9, 31, v8
	v_ashrrev_i32_e32 v11, 31, v10
	v_ashrrev_i32_e32 v21, 31, v20
	v_ashrrev_i32_e32 v23, 31, v22
	v_ashrrev_i32_e32 v33, 31, v32
	v_ashrrev_i32_e32 v31, 31, v30
	v_lshl_add_u64 v[2:3], v[2:3], 1, v[28:29]
	v_lshl_add_u64 v[8:9], v[8:9], 1, v[28:29]
	v_lshl_add_u64 v[10:11], v[10:11], 1, v[28:29]
	v_lshl_add_u64 v[20:21], v[20:21], 1, v[28:29]
	v_lshl_add_u64 v[22:23], v[22:23], 1, v[28:29]
	v_lshl_add_u64 v[32:33], v[32:33], 1, v[28:29]
	v_lshl_add_u64 v[28:29], v[30:31], 1, v[28:29]
	global_load_dwordx4 v[4:7], v[0:1], off
	s_nop 0
	global_load_dwordx4 v[0:3], v[2:3], off
	s_nop 0
	global_load_dwordx4 v[12:15], v[8:9], off
	s_nop 0
	global_load_dwordx4 v[8:11], v[10:11], off
	s_nop 0
	global_load_dwordx4 v[24:27], v[20:21], off
	s_nop 0
	global_load_dwordx4 v[20:23], v[22:23], off
	s_nop 0
	global_load_dwordx4 v[32:35], v[32:33], off
	s_nop 0
	global_load_dwordx4 v[28:31], v[28:29], off
	s_mov_b64 s[10:11], 0
	s_branch .LBB0_2179
